# static s_setprio 1 for waves 4-7 at kernel entry (younger-half priority raise), rest unchanged from v33
# speedup vs baseline: 1.0012x; 1.0006x over previous
; #define LAS __attribute__((address_space(3)))
; __device__ __forceinline__ int opaque_tid() { int t = threadIdx.x; asm volatile("" : "+v"(t)); return t; }
; __device__ __forceinline__ unsigned xb_add(unsigned* p, unsigned v) { return __hip_atomic_fetch_add(p, v, __ATOMIC_RELAXED, __HIP_MEMORY_SCOPE_AGENT); }
; __device__ __forceinline__ unsigned xb_xcc_id() { return (unsigned)__builtin_amdgcn_s_getreg((3 << 11) | 20) & 0xFu; }
; __device__ __forceinline__ XcdBarrier xcd_barrier_post(unsigned* bar, volatile LAS unsigned* st) {
;     XcdBarrier b; b.bar = bar; b.x = xb_xcc_id(); b.st = st;
;     if (threadIdx.x == 0) st[10] = xb_add(&bar[XB_XCNT(b.x)], 1u);
;     return b;
; __global__ void __launch_bounds__(NWAVES * 64, 2) fwd_megakernel(Args args) {
;     extern __shared__ __attribute__((aligned(16))) unsigned char lds_raw[];
;     LAS unsigned char* lds = (LAS unsigned char*)lds_raw;
;     cg::grid_group grid = cg::this_grid();
;     int tid = opaque_tid(), lane = tid & 63, wave = __builtin_amdgcn_readfirstlane(tid >> 6);
;     const int G = gridDim.x; int bid = blockIdx.x;
;     ...
;     unsigned char* ws = args.ws;
;     float* SS = (float*)(ws + WS_CTL + CTL_SS_OFF);
;     bf16_t* WB = (bf16_t*)(ws + WS_W);
;     float* X = (float*)(ws + WS_X);
;     bf16_t* H = (bf16_t*)(ws + WS_H);
;     bf16_t* BIG = (bf16_t*)(ws + WS_BIG);
;     bf16_t* AO = (bf16_t*)(ws + WS_AO);
;     bf16_t* QM = (bf16_t*)(ws + WS_QM);
;     bf16_t* O2 = (bf16_t*)(ws + WS_O2);
;     bf16_t* KVB = (bf16_t*)(ws + WS_KV);
;     bf16_t* MEMN = (bf16_t*)(ws + WS_MEMN);
;     float* OST = (float*)(ws + WS_OST);
;     float* MST = (float*)(ws + WS_ML);
;     float* LST = MST + (size_t)SEQ * 16;
;     constexpr int CW_BAR = 4096;
;     volatile LAS unsigned* bst = (volatile LAS unsigned*)(lds + LDS_BYTES - 64);
;     if (tid < 16) bst[tid] = 0u;
;     __syncthreads();
;     XcdBarrier xbar = xcd_barrier_post((unsigned*)(ws + WS_CTL) + CW_BAR, bst);
_Z14fwd_megakernel4Args:
	s_load_dwordx8 s[36:43], s[0:1], 0xc0
	s_load_dword s3, s[0:1], 0xe0
	v_and_b32_e32 v232, 0x3ff, v0
	s_add_u32 s6, s0, 0xd8
	v_mov_b32_e32 v1, v232
	s_addc_u32 s7, s1, 0
	s_nop 0
	v_readfirstlane_b32 s14, v1
	s_cmpk_lt_u32 s14, 0x100
	s_cbranch_scc1 .Lprio_lo
	s_setprio 1
.Lprio_lo:
	v_cmp_gt_i32_e32 vcc, 16, v1
	s_and_saveexec_b64 s[4:5], vcc
	v_lshl_add_u32 v2, v1, 2, 0
	v_add_u32_e32 v2, 0x23fc0, v2
	v_mov_b32_e32 v3, 0
	ds_write_b32 v2, v3
	s_or_b64 exec, exec, s[4:5]
	s_waitcnt lgkmcnt(0)
	s_barrier
	s_add_u32 s4, s40, 0x4000
	s_getreg_b32 s8, hwreg(HW_REG_XCC_ID, 0, 4)
	s_addc_u32 s5, s41, 0
	s_and_b32 s16, s8, 15
	v_cmp_eq_u32_e64 s[10:11], 0, v232
	s_mov_b64 s[8:9], exec
	s_nop 0
	v_writelane_b32 v251, s10, 0
	s_nop 1
	v_writelane_b32 v251, s11, 1
	s_and_b64 s[10:11], s[8:9], s[10:11]
	s_mov_b64 exec, s[10:11]
	s_cbranch_execz .LBB0_6
	s_mov_b64 s[12:13], exec
	v_mbcnt_lo_u32_b32 v2, s12, 0
	v_mbcnt_hi_u32_b32 v2, s13, v2
	v_cmp_eq_u32_e32 vcc, 0, v2
	s_and_saveexec_b64 s[10:11], vcc
	s_cbranch_execz .LBB0_5
	s_lshl_b32 s15, s16, 8
	s_bcnt1_i32_b64 s12, s[12:13]
	v_mov_b32_e32 v3, s15
	v_mov_b32_e32 v4, s12
	global_atomic_add v3, v3, v4, s[4:5] offset:1024 sc0
